# stacked: GLA summary kv loop unrolled, zero-weight gate-tile MFMA blocks skipped, prep phase order alternated per workgroup
# baseline (speedup 1.0000x reference)
; #define LBAR do { asm volatile("s_waitcnt lgkmcnt(0)" ::: "memory"); __builtin_amdgcn_s_barrier(); } while (0)
; __device__ __forceinline__ void gla_summ_unit(const P& p, int unit, const SummRaw& raw) {
;     ...
;   LBAR;
;   u16* kvout = (u16*)((char*)p.out + OUT_KV);
;   int fr = lane & 15, fq = lane >> 4;
; #pragma unroll 1
;   for (int tI = 0; tI < 8; ++tI) {
;     int tile = wid * 8 + tI;
;     int dir = tile >> 5, dkt = (tile >> 3) & 3, dvt = tile & 7;
;     const u16* Asrc = (dir ? kdbT : kdfT) + (dkt * 16 + fr) * LP + fq * 8;
;     const u16* Bsrc = vT + (dvt * 16 + fr) * LP + fq * 8;
;     f32x4 d = {0.f, 0.f, 0.f, 0.f};
; #pragma unroll
;     for (int ks = 0; ks < 2; ++ks) {
;       bf16x8 a = *(const bf16x8*)(Asrc + ks * 32);
;       bf16x8 b = *(const bf16x8*)(Bsrc + ks * 32);
;       d = __builtin_amdgcn_mfma_f32_16x16x32_bf16(a, b, d, 0, 0, 0);
;     }
;     uint2 w; w.x = pack2(d[0], d[1]); w.y = pack2(d[2], d[3]);
;     *(uint2*)(kvout + (size_t)(unit * 2 + dir) * 8192 + (dvt * 16 + fr) * 64 + dkt * 16 + fq * 4) = w;
;   }
; __device__ void phase_gla_summ(const P& p) {
;     ...
;   for (; u < 4096; u += gridDim.x) {
;     int un = u + gridDim.x;
;     SummRaw nxt = gla_summ_load(p, un < 4096 ? un : u, tid);
;     gla_summ_unit(p, u, cur);
;     cur = nxt;
;   }
.LBB0_226:
	s_or_b64 exec, exec, s[26:27]
	v_and_b32_e32 v31, 15, v51
	v_cmp_gt_u32_e32 vcc, s40, v43
	v_lshlrev_b32_e32 v9, 4, v45
	v_ashrrev_i32_e32 v44, 8, v43
	v_cndmask_b32_e32 v8, v49, v50, vcc
	v_and_or_b32 v9, v9, 48, v31
	s_ashr_i32 s21, s20, 31
	v_add_u32_e32 v8, 16, v8
	v_mul_u32_u24_e32 v9, 0x90, v9
	v_and_b32_e32 v28, 48, v28
	v_mul_u32_u24_e32 v29, 0x90, v31
	v_ashrrev_i32_e32 v45, 31, v44
	v_add3_u32 v12, v8, v9, v28
	v_add3_u32 v30, v29, v28, 16
	v_lshl_add_u64 v[28:29], v[44:45], 0, s[20:21]
	s_waitcnt lgkmcnt(0)
	s_barrier
	ds_read_b128 v[8:11], v12
	ds_read_b128 v[12:15], v12 offset:64
	v_lshlrev_b64 v[28:29], 14, v[28:29]
	v_lshl_or_b32 v28, v31, 4, v28
	v_lshrrev_b32_e32 v31, 1, v43
	v_and_b32_e32 v34, 48, v51
	v_and_b32_e32 v31, 0x60, v31
	v_lshrrev_b32_e32 v34, 1, v34
	v_lshlrev_b32_e32 v31, 4, v31
	v_and_b32_e32 v45, 16, v34
	v_and_b32_e32 v34, 8, v34
	v_lshlrev_b32_e32 v45, 4, v45
	v_or3_b32 v28, v28, v31, v34
	v_or_b32_e32 v28, v28, v45
	v_lshl_add_u64 v[28:29], s[10:11], 0, v[28:29]
	v_add_u32_e32 v34, 0x11200, v30
	ds_read_b128 v[80:83], v34
	ds_read_b128 v[84:87], v34 offset:64
	ds_read_b128 v[88:91], v34 offset:2304
	ds_read_b128 v[92:95], v34 offset:2368
	ds_read_b128 v[96:99], v34 offset:4608
	ds_read_b128 v[100:103], v34 offset:4672
	ds_read_b128 v[104:107], v34 offset:6912
	ds_read_b128 v[108:111], v34 offset:6976
	ds_read_b128 v[112:115], v34 offset:9216
	ds_read_b128 v[116:119], v34 offset:9280
	ds_read_b128 v[120:123], v34 offset:11520
	ds_read_b128 v[124:127], v34 offset:11584
	s_waitcnt lgkmcnt(10)
	v_mfma_f32_16x16x32_bf16 v[80:83], v[8:11], v[80:83], 0
	v_mfma_f32_16x16x32_bf16 v[80:83], v[12:15], v[84:87], v[80:83]
	s_waitcnt lgkmcnt(8)
	v_mfma_f32_16x16x32_bf16 v[88:91], v[8:11], v[88:91], 0
	v_mfma_f32_16x16x32_bf16 v[88:91], v[12:15], v[92:95], v[88:91]
	ds_read_b128 v[128:131], v34 offset:13824
	ds_read_b128 v[132:135], v34 offset:13888
	s_waitcnt lgkmcnt(8)
	v_mfma_f32_16x16x32_bf16 v[96:99], v[8:11], v[96:99], 0
	v_mfma_f32_16x16x32_bf16 v[96:99], v[12:15], v[100:103], v[96:99]
	ds_read_b128 v[136:139], v34 offset:16128
	ds_read_b128 v[140:143], v34 offset:16192
	s_waitcnt lgkmcnt(8)
	v_mfma_f32_16x16x32_bf16 v[104:107], v[8:11], v[104:107], 0
	v_mfma_f32_16x16x32_bf16 v[104:107], v[12:15], v[108:111], v[104:107]
	s_waitcnt lgkmcnt(6)
	v_mfma_f32_16x16x32_bf16 v[112:115], v[8:11], v[112:115], 0
	v_mfma_f32_16x16x32_bf16 v[112:115], v[12:15], v[116:119], v[112:115]
	s_waitcnt lgkmcnt(4)
	v_mfma_f32_16x16x32_bf16 v[120:123], v[8:11], v[120:123], 0
	v_mfma_f32_16x16x32_bf16 v[120:123], v[12:15], v[124:127], v[120:123]
	s_waitcnt lgkmcnt(2)
	v_mfma_f32_16x16x32_bf16 v[128:131], v[8:11], v[128:131], 0
	v_mfma_f32_16x16x32_bf16 v[128:131], v[12:15], v[132:135], v[128:131]
	s_waitcnt lgkmcnt(0)
	v_mfma_f32_16x16x32_bf16 v[136:139], v[8:11], v[136:139], 0
	v_mfma_f32_16x16x32_bf16 v[136:139], v[12:15], v[140:143], v[136:139]
	v_cvt_pk_bf16_f32 v80, v80, v81
	v_cvt_pk_bf16_f32 v81, v82, v83
	global_store_dwordx2 v[28:29], v[80:81], off offset:-4
	v_lshl_add_u64 v[28:29], v[28:29], 0, s[22:23]
	v_cvt_pk_bf16_f32 v88, v88, v89
	v_cvt_pk_bf16_f32 v89, v90, v91
	global_store_dwordx2 v[28:29], v[88:89], off offset:-4
	v_lshl_add_u64 v[28:29], v[28:29], 0, s[22:23]
	v_cvt_pk_bf16_f32 v96, v96, v97
	v_cvt_pk_bf16_f32 v97, v98, v99
	global_store_dwordx2 v[28:29], v[96:97], off offset:-4
	v_lshl_add_u64 v[28:29], v[28:29], 0, s[22:23]
	v_cvt_pk_bf16_f32 v104, v104, v105
	v_cvt_pk_bf16_f32 v105, v106, v107
	global_store_dwordx2 v[28:29], v[104:105], off offset:-4
	v_lshl_add_u64 v[28:29], v[28:29], 0, s[22:23]
	v_cvt_pk_bf16_f32 v112, v112, v113
	v_cvt_pk_bf16_f32 v113, v114, v115
	global_store_dwordx2 v[28:29], v[112:113], off offset:-4
	v_lshl_add_u64 v[28:29], v[28:29], 0, s[22:23]
	v_cvt_pk_bf16_f32 v120, v120, v121
	v_cvt_pk_bf16_f32 v121, v122, v123
	global_store_dwordx2 v[28:29], v[120:121], off offset:-4
	v_lshl_add_u64 v[28:29], v[28:29], 0, s[22:23]
	v_cvt_pk_bf16_f32 v128, v128, v129
	v_cvt_pk_bf16_f32 v129, v130, v131
	global_store_dwordx2 v[28:29], v[128:129], off offset:-4
	v_lshl_add_u64 v[28:29], v[28:29], 0, s[22:23]
	v_cvt_pk_bf16_f32 v136, v136, v137
	v_cvt_pk_bf16_f32 v137, v138, v139
	global_store_dwordx2 v[28:29], v[136:137], off offset:-4
	v_lshl_add_u64 v[28:29], v[28:29], 0, s[22:23]
	s_waitcnt lgkmcnt(0)
	s_add_i32 s20, s20, s3
	s_andn2_b64 vcc, exec, s[24:25]
	s_mov_b32 s21, s46
	s_waitcnt vmcnt(3)
	v_mov_b64_e32 v[12:13], v[20:21]
	v_mov_b64_e32 v[14:15], v[22:23]
	s_waitcnt vmcnt(1)
	v_mov_b64_e32 v[8:9], v[24:25]
	v_mov_b64_e32 v[10:11], v[26:27]
	v_mov_b64_e32 v[28:29], v[16:17]
	v_mov_b64_e32 v[30:31], v[18:19]
	s_barrier
	s_cbranch_vccnz .LBB0_224
